# also skip the final grid barrier after the last step (kernel end)
# speedup vs baseline: 1.0028x; 1.0028x over previous
.LBB0_372:
	s_waitcnt vmcnt(0)
	s_waitcnt vmcnt(0) lgkmcnt(0)
	s_barrier
	s_mov_b64 s[0:1], exec
	s_cmp_eq_u32 s44, 16
	s_cbranch_scc1 .LBB0_17
	s_cmp_eq_u32 s44, 32
	s_cbranch_scc1 .LBB0_17
	s_cmp_eq_u32 s44, 48
	s_cbranch_scc1 .LBB0_17
	v_readlane_b32 s2, v253, 24
	v_readlane_b32 s3, v253, 25
	s_and_b64 s[2:3], s[0:1], s[2:3]
	s_mov_b64 exec, s[2:3]
	s_cbranch_execz .LBB0_17
	v_readlane_b32 s2, v252, 11
	s_waitcnt vmcnt(0) expcnt(0) lgkmcnt(0)
	s_nop 0
	v_mov_b32_e32 v1, s2
	ds_read_b32 v3, v1
	v_readlane_b32 s2, v252, 12
	s_waitcnt lgkmcnt(0)
	v_cmp_ne_u32_e32 vcc, 0, v3
	v_mov_b32_e32 v1, s2
	ds_read_b32 v2, v1
	s_cbranch_vccnz .LBB0_388
	s_mov_b32 s2, 1
	s_branch .LBB0_376
